# WKV waves skip the common loop top: next-chunk global loads issued inside the WKV block behind the LDS prologue reads
# baseline (speedup 1.0000x reference)
; #define SCAN_ISSUE(t0) do { _Pragma("unroll") for (int j = 0; j < 3; ++j) { const bf16* src = (isW ? (pp[j] < 32 ? SA : SB) : PB) + so[j]; \
;             if (j < 2 || v2ok) pre[j] = *(const v4u*)src; so[j] += isW ? (pp[j] < 32 ? TC * 2048 : TC * 1024) : TC * APROJ; } } while (0)
; #define SCAN_COMMIT(bi) do { _Pragma("unroll") for (int j = 0; j < 3; ++j) { if (j < 2 || v2ok) { \
;             if (isW) st8n(bufW + ((bi) * TC + ps[j]) * SCW + pp[j] * 8, pre[j]); else st8n(bufG + ((bi) * TC + ps[j]) * SCG + pp[j] * 8, pre[j]); } } } while (0)
; __device__ __forceinline__ void scan_phase(const Args& a, int e, LAS unsigned char* lds) {
;     ...
;         __syncthreads();
;         SCAN_ISSUE(0); SCAN_COMMIT(0);
;         __syncthreads();
; #pragma unroll 1
;         for (int c = 0; c < nc; ++c) {
;             const int bi = c & 1;
;             if (c + 1 < nc) SCAN_ISSUE((c + 1) * TC);
.LBB0_233:
	s_add_i32 s11, s14, 1
	s_cmp_lt_u32 s11, s10
	s_cselect_b64 vcc, -1, 0
	s_cmp_eq_u64 s[40:41], 0
	s_cbranch_scc1 .Lwkv_fast
	s_cmp_ge_u32 s11, s10
	s_cbranch_scc1 .LBB0_237
	v_mov_b32_e32 v21, v1
	s_waitcnt vmcnt(2)
	v_lshl_add_u64 v[6:7], v[0:1], 1, v[36:37]
	s_waitcnt vmcnt(1)
	v_lshl_add_u64 v[10:11], v[20:21], 1, v[38:39]
	global_load_dwordx4 v[6:9], v[6:7], off
	s_nop 0
	global_load_dwordx4 v[10:13], v[10:11], off
	s_and_saveexec_b64 s[12:13], s[0:1]
	s_cbranch_execz .LBB0_236
	v_mov_b32_e32 v19, v1
	v_lshl_add_u64 v[2:3], v[18:19], 1, v[40:41]
	global_load_dwordx4 v[2:5], v[2:3], off

; #define SCAN_ISSUE(t0) do { _Pragma("unroll") for (int j = 0; j < 3; ++j) { const bf16* src = (isW ? (pp[j] < 32 ? SA : SB) : PB) + so[j]; \
;             if (j < 2 || v2ok) pre[j] = *(const v4u*)src; so[j] += isW ? (pp[j] < 32 ? TC * 2048 : TC * 1024) : TC * APROJ; } } while (0)
; __device__ __forceinline__ void scan_phase(const Args& a, int e, LAS unsigned char* lds) {
;     ...
;             const int bi = c & 1;
;             if (c + 1 < nc) SCAN_ISSUE((c + 1) * TC);
;             float oacc = 0.f; float op[16];
;             if (isW) {
.Lwkv_fast:
	s_and_b32 s14, s14, 1
	s_mov_b64 s[12:13], 0
	s_branch .LBB0_240

; #define LAS __attribute__((address_space(3)))
; #define LO2(v4) (__builtin_shufflevector(v4, v4, 0, 1))
; #define HI2(v4) (__builtin_shufflevector(v4, v4, 2, 3))
; __device__ __forceinline__ f32x2 fma2(f32x2 a, f32x2 b, f32x2 c) { return __builtin_elementwise_fma(a, b, c); }
; #define WKV_LOAD(d, s) do { const LAS float* p_ = bw + (s) * SCW; d.r = *(const LAS f32x4*)(p_); d.u = *(const LAS f32x4*)(p_ + 64); d.km = *(const LAS f32x4*)(p_ + 128); \
;                     d.kk = *(const LAS f32x4*)(p_ + 256); d.ka = *(const LAS f32x4*)(p_ + 320); d.v = bv[(s) * SCW]; } while (0)
; __device__ __forceinline__ void scan_phase(const Args& a, int e, LAS unsigned char* lds) {
;     ...
;                 const LAS float* bw = bufW + bi * TC * SCW + 4 * g; const LAS float* bv = bufW + bi * TC * SCW + 192 + vrow;
;     ...
;                 WkvIn in[3];
;                 WKV_LOAD(in[0], 0); WKV_LOAD(in[1], 1);
; #pragma unroll
;                 for (int s = 0; s < TC; ++s) {
;                     if (s + 2 < TC) WKV_LOAD(in[(s + 2) % 3], s + 2);
;                     __builtin_amdgcn_sched_barrier(0);
;                     const WkvIn& x = in[s % 3];
;                     const f32x2 vv = {x.v, x.v};
;                     const f32x2 s2 = fma2(P1, HI2(x.kk), P0 * LO2(x.kk));
;                     const f32x2 T0 = fma2(vv, LO2(x.km), fma2(-LO2(x.u), P0, P0)), T1 = fma2(vv, HI2(x.km), fma2(-HI2(x.u), P1, P1));
;                     const float sa = rowsum16(s2.x + s2.y);
;                     const f32x2 ns = {-sa, -sa};
;                     P0 = fma2(ns, LO2(x.ka), T0); P1 = fma2(ns, HI2(x.ka), T1);
;                     const f32x2 o2 = fma2(P1, HI2(x.r), P0 * LO2(x.r));
;                     op[s] = o2.x + o2.y;
;                 }
.LBB0_240:
	s_mul_i32 s15, s14, 0x6000
	v_or_b32_e32 v22, s15, v55
	v_lshl_or_b32 v23, v77, 2, s15
	ds_read_b128 v[122:125], v22 offset:0
	ds_read_b128 v[86:89], v22 offset:256
	ds_read_b128 v[102:105], v22 offset:512
	ds_read_b128 v[78:81], v22 offset:1024
	ds_read_b128 v[110:113], v22 offset:1280
	ds_read_b32 v136, v23 offset:768
	ds_read_b128 v[126:129], v22 offset:1536
	ds_read_b128 v[98:101], v22 offset:1792
	ds_read_b128 v[106:109], v22 offset:2048
	ds_read_b128 v[82:85], v22 offset:2560
	ds_read_b128 v[114:117], v22 offset:2816
	ds_read_b32 v138, v23 offset:2304
	s_cbranch_vccz .Lwkv_noload
	v_mov_b32_e32 v21, v1
	v_lshl_add_u64 v[6:7], v[0:1], 1, v[36:37]
	v_lshl_add_u64 v[10:11], v[20:21], 1, v[38:39]
	global_load_dwordx4 v[6:9], v[6:7], off
	v_mov_b32_e32 v19, v1
	global_load_dwordx4 v[10:13], v[10:11], off
	v_lshl_add_u64 v[2:3], v[18:19], 1, v[40:41]
	global_load_dwordx4 v[2:5], v[2:3], off
	v_add_u32_e32 v0, v0, v65
	v_add_u32_e32 v20, v20, v66
	v_add_u32_e32 v18, v18, v64
.Lwkv_noload:
	s_waitcnt lgkmcnt(6)
	v_pk_mul_f32 v[90:91], v[14:15], v[78:79]
	v_pk_fma_f32 v[94:95], v[86:87], v[14:15], v[14:15] neg_lo:[1,0,0] neg_hi:[1,0,0]
	v_pk_fma_f32 v[90:91], v[16:17], v[80:81], v[90:91]
	v_pk_fma_f32 v[134:135], v[88:89], v[16:17], v[16:17] neg_lo:[1,0,0] neg_hi:[1,0,0]
	v_add_f32_e32 v50, v90, v91
	v_pk_fma_f32 v[94:95], v[136:137], v[102:103], v[94:95] op_sel_hi:[0,1,1]
	v_pk_fma_f32 v[134:135], v[136:137], v[104:105], v[134:135] op_sel_hi:[0,1,1]
	v_add_f32_dpp v50, v50, v50 row_ror:8 row_mask:0xf bank_mask:0xf bound_ctrl:1
	ds_read_b128 v[130:133], v22 offset:3072
	ds_read_b128 v[86:89], v22 offset:3328
	v_add_f32_dpp v50, v50, v50 row_ror:4 row_mask:0xf bank_mask:0xf bound_ctrl:1
	ds_read_b128 v[102:105], v22 offset:3584
	ds_read_b128 v[78:81], v22 offset:4096
	v_add_f32_dpp v50, v50, v50 row_ror:2 row_mask:0xf bank_mask:0xf bound_ctrl:1
	ds_read_b128 v[118:121], v22 offset:4352
	ds_read_b32 v136, v23 offset:3840
	v_add_f32_dpp v50, v50, v50 row_ror:1 row_mask:0xf bank_mask:0xf bound_ctrl:1
	v_pk_fma_f32 v[14:15], v[50:51], v[110:111], v[94:95] op_sel_hi:[0,1,1] neg_lo:[1,0,0] neg_hi:[1,0,0]
	v_pk_fma_f32 v[16:17], v[50:51], v[112:113], v[134:135] op_sel_hi:[0,1,1] neg_lo:[1,0,0] neg_hi:[1,0,0]
	v_pk_mul_f32 v[94:95], v[14:15], v[122:123]
	s_waitcnt lgkmcnt(6)
	v_pk_mul_f32 v[90:91], v[14:15], v[82:83]
	v_pk_fma_f32 v[94:95], v[16:17], v[124:125], v[94:95]
	v_pk_fma_f32 v[90:91], v[16:17], v[84:85], v[90:91]
	v_add_f32_e32 v19, v94, v95
	v_pk_fma_f32 v[94:95], v[98:99], v[14:15], v[14:15] neg_lo:[1,0,0] neg_hi:[1,0,0]
	v_pk_fma_f32 v[134:135], v[100:101], v[16:17], v[16:17] neg_lo:[1,0,0] neg_hi:[1,0,0]
	v_add_f32_e32 v50, v90, v91
	v_pk_fma_f32 v[94:95], v[138:139], v[106:107], v[94:95] op_sel_hi:[0,1,1]
	v_pk_fma_f32 v[134:135], v[138:139], v[108:109], v[134:135] op_sel_hi:[0,1,1]
	v_add_f32_dpp v50, v50, v50 row_ror:8 row_mask:0xf bank_mask:0xf bound_ctrl:1
	ds_read_b128 v[122:125], v22 offset:4608
	ds_read_b128 v[98:101], v22 offset:4864
	v_add_f32_dpp v50, v50, v50 row_ror:4 row_mask:0xf bank_mask:0xf bound_ctrl:1
	ds_read_b128 v[106:109], v22 offset:5120
	ds_read_b128 v[82:85], v22 offset:5632
	v_add_f32_dpp v50, v50, v50 row_ror:2 row_mask:0xf bank_mask:0xf bound_ctrl:1
	ds_read_b128 v[110:113], v22 offset:5888
	ds_read_b32 v138, v23 offset:5376
	v_add_f32_dpp v50, v50, v50 row_ror:1 row_mask:0xf bank_mask:0xf bound_ctrl:1
	v_pk_fma_f32 v[14:15], v[50:51], v[114:115], v[94:95] op_sel_hi:[0,1,1] neg_lo:[1,0,0] neg_hi:[1,0,0]
	v_pk_fma_f32 v[16:17], v[50:51], v[116:117], v[134:135] op_sel_hi:[0,1,1] neg_lo:[1,0,0] neg_hi:[1,0,0]
	v_pk_mul_f32 v[94:95], v[14:15], v[126:127]
	s_waitcnt lgkmcnt(6)
	v_pk_mul_f32 v[90:91], v[14:15], v[78:79]
	v_pk_fma_f32 v[94:95], v[16:17], v[128:129], v[94:95]
	v_pk_fma_f32 v[90:91], v[16:17], v[80:81], v[90:91]
	v_add_f32_e32 v21, v94, v95
	v_pk_fma_f32 v[94:95], v[86:87], v[14:15], v[14:15] neg_lo:[1,0,0] neg_hi:[1,0,0]
	v_pk_fma_f32 v[134:135], v[88:89], v[16:17], v[16:17] neg_lo:[1,0,0] neg_hi:[1,0,0]
	v_add_f32_e32 v50, v90, v91
	v_pk_fma_f32 v[94:95], v[136:137], v[102:103], v[94:95] op_sel_hi:[0,1,1]
	v_pk_fma_f32 v[134:135], v[136:137], v[104:105], v[134:135] op_sel_hi:[0,1,1]
	v_add_f32_dpp v50, v50, v50 row_ror:8 row_mask:0xf bank_mask:0xf bound_ctrl:1
	ds_read_b128 v[126:129], v22 offset:6144
	ds_read_b128 v[86:89], v22 offset:6400
	v_add_f32_dpp v50, v50, v50 row_ror:4 row_mask:0xf bank_mask:0xf bound_ctrl:1
	ds_read_b128 v[102:105], v22 offset:6656
	ds_read_b128 v[78:81], v22 offset:7168
	v_add_f32_dpp v50, v50, v50 row_ror:2 row_mask:0xf bank_mask:0xf bound_ctrl:1
	ds_read_b128 v[114:117], v22 offset:7424
	ds_read_b32 v136, v23 offset:6912
	v_add_f32_dpp v50, v50, v50 row_ror:1 row_mask:0xf bank_mask:0xf bound_ctrl:1
	v_pk_fma_f32 v[14:15], v[50:51], v[118:119], v[94:95] op_sel_hi:[0,1,1] neg_lo:[1,0,0] neg_hi:[1,0,0]
	v_pk_fma_f32 v[16:17], v[50:51], v[120:121], v[134:135] op_sel_hi:[0,1,1] neg_lo:[1,0,0] neg_hi:[1,0,0]
	v_pk_mul_f32 v[94:95], v[14:15], v[130:131]
	s_waitcnt lgkmcnt(6)
; #define LO2(v4) (__builtin_shufflevector(v4, v4, 0, 1))
; #define HI2(v4) (__builtin_shufflevector(v4, v4, 2, 3))
; __device__ __forceinline__ f32x2 fma2(f32x2 a, f32x2 b, f32x2 c) { return __builtin_elementwise_fma(a, b, c); }
; #define WKV_LOAD(d, s) do { const LAS float* p_ = bw + (s) * SCW; d.r = *(const LAS f32x4*)(p_); d.u = *(const LAS f32x4*)(p_ + 64); d.km = *(const LAS f32x4*)(p_ + 128); \
;                     d.kk = *(const LAS f32x4*)(p_ + 256); d.ka = *(const LAS f32x4*)(p_ + 320); d.v = bv[(s) * SCW]; } while (0)
; __device__ __forceinline__ void scan_phase(const Args& a, int e, LAS unsigned char* lds) {
;     ...
;                 for (int s = 0; s < TC; ++s) {
;                     if (s + 2 < TC) WKV_LOAD(in[(s + 2) % 3], s + 2);
;                     __builtin_amdgcn_sched_barrier(0);
;                     const WkvIn& x = in[s % 3];
;                     const f32x2 vv = {x.v, x.v};
;                     const f32x2 s2 = fma2(P1, HI2(x.kk), P0 * LO2(x.kk));
;                     const f32x2 T0 = fma2(vv, LO2(x.km), fma2(-LO2(x.u), P0, P0)), T1 = fma2(vv, HI2(x.km), fma2(-HI2(x.u), P1, P1));
;                     const float sa = rowsum16(s2.x + s2.y);
;                     const f32x2 ns = {-sa, -sa};
;                     P0 = fma2(ns, LO2(x.ka), T0); P1 = fma2(ns, HI2(x.ka), T1);
;                     const f32x2 o2 = fma2(P1, HI2(x.r), P0 * LO2(x.r));
;                     op[s] = o2.x + o2.y;
;                 }
	v_pk_mul_f32 v[90:91], v[14:15], v[82:83]
	v_pk_fma_f32 v[94:95], v[16:17], v[132:133], v[94:95]
	v_pk_fma_f32 v[90:91], v[16:17], v[84:85], v[90:91]
	v_add_f32_e32 v24, v94, v95
	v_pk_fma_f32 v[94:95], v[98:99], v[14:15], v[14:15] neg_lo:[1,0,0] neg_hi:[1,0,0]
	v_pk_fma_f32 v[134:135], v[100:101], v[16:17], v[16:17] neg_lo:[1,0,0] neg_hi:[1,0,0]
	v_add_f32_e32 v50, v90, v91
	v_pk_fma_f32 v[94:95], v[138:139], v[106:107], v[94:95] op_sel_hi:[0,1,1]
	v_pk_fma_f32 v[134:135], v[138:139], v[108:109], v[134:135] op_sel_hi:[0,1,1]
	v_add_f32_dpp v50, v50, v50 row_ror:8 row_mask:0xf bank_mask:0xf bound_ctrl:1
	ds_read_b128 v[130:133], v22 offset:7680
	ds_read_b128 v[98:101], v22 offset:7936
	v_add_f32_dpp v50, v50, v50 row_ror:4 row_mask:0xf bank_mask:0xf bound_ctrl:1
	ds_read_b128 v[106:109], v22 offset:8192
	ds_read_b128 v[82:85], v22 offset:8704
	v_add_f32_dpp v50, v50, v50 row_ror:2 row_mask:0xf bank_mask:0xf bound_ctrl:1
	ds_read_b128 v[118:121], v22 offset:8960
	ds_read_b32 v138, v23 offset:8448
	v_add_f32_dpp v50, v50, v50 row_ror:1 row_mask:0xf bank_mask:0xf bound_ctrl:1
	v_pk_fma_f32 v[14:15], v[50:51], v[110:111], v[94:95] op_sel_hi:[0,1,1] neg_lo:[1,0,0] neg_hi:[1,0,0]
	v_pk_fma_f32 v[16:17], v[50:51], v[112:113], v[134:135] op_sel_hi:[0,1,1] neg_lo:[1,0,0] neg_hi:[1,0,0]
	v_pk_mul_f32 v[94:95], v[14:15], v[122:123]
	s_waitcnt lgkmcnt(6)
	v_pk_mul_f32 v[90:91], v[14:15], v[78:79]
	v_pk_fma_f32 v[94:95], v[16:17], v[124:125], v[94:95]
	v_pk_fma_f32 v[90:91], v[16:17], v[80:81], v[90:91]
	v_add_f32_e32 v25, v94, v95
	v_pk_fma_f32 v[94:95], v[86:87], v[14:15], v[14:15] neg_lo:[1,0,0] neg_hi:[1,0,0]
	v_pk_fma_f32 v[134:135], v[88:89], v[16:17], v[16:17] neg_lo:[1,0,0] neg_hi:[1,0,0]
	v_add_f32_e32 v50, v90, v91
	v_pk_fma_f32 v[94:95], v[136:137], v[102:103], v[94:95] op_sel_hi:[0,1,1]
	v_pk_fma_f32 v[134:135], v[136:137], v[104:105], v[134:135] op_sel_hi:[0,1,1]
	v_add_f32_dpp v50, v50, v50 row_ror:8 row_mask:0xf bank_mask:0xf bound_ctrl:1
	ds_read_b128 v[122:125], v22 offset:9216
	ds_read_b128 v[86:89], v22 offset:9472
	v_add_f32_dpp v50, v50, v50 row_ror:4 row_mask:0xf bank_mask:0xf bound_ctrl:1
	ds_read_b128 v[102:105], v22 offset:9728
	ds_read_b128 v[78:81], v22 offset:10240
	v_add_f32_dpp v50, v50, v50 row_ror:2 row_mask:0xf bank_mask:0xf bound_ctrl:1
	ds_read_b128 v[110:113], v22 offset:10496
	ds_read_b32 v136, v23 offset:9984
	v_add_f32_dpp v50, v50, v50 row_ror:1 row_mask:0xf bank_mask:0xf bound_ctrl:1
	v_pk_fma_f32 v[14:15], v[50:51], v[114:115], v[94:95] op_sel_hi:[0,1,1] neg_lo:[1,0,0] neg_hi:[1,0,0]
	v_pk_fma_f32 v[16:17], v[50:51], v[116:117], v[134:135] op_sel_hi:[0,1,1] neg_lo:[1,0,0] neg_hi:[1,0,0]
	v_pk_mul_f32 v[94:95], v[14:15], v[126:127]
	s_waitcnt lgkmcnt(6)
	v_pk_mul_f32 v[90:91], v[14:15], v[82:83]
	v_pk_fma_f32 v[94:95], v[16:17], v[128:129], v[94:95]
	v_pk_fma_f32 v[90:91], v[16:17], v[84:85], v[90:91]
	v_add_f32_e32 v43, v94, v95
	v_pk_fma_f32 v[94:95], v[98:99], v[14:15], v[14:15] neg_lo:[1,0,0] neg_hi:[1,0,0]
	v_pk_fma_f32 v[134:135], v[100:101], v[16:17], v[16:17] neg_lo:[1,0,0] neg_hi:[1,0,0]
	v_add_f32_e32 v50, v90, v91
	v_pk_fma_f32 v[94:95], v[138:139], v[106:107], v[94:95] op_sel_hi:[0,1,1]
	v_pk_fma_f32 v[134:135], v[138:139], v[108:109], v[134:135] op_sel_hi:[0,1,1]
	v_add_f32_dpp v50, v50, v50 row_ror:8 row_mask:0xf bank_mask:0xf bound_ctrl:1
	ds_read_b128 v[126:129], v22 offset:10752
	ds_read_b128 v[98:101], v22 offset:11008
	v_add_f32_dpp v50, v50, v50 row_ror:4 row_mask:0xf bank_mask:0xf bound_ctrl:1
	ds_read_b128 v[106:109], v22 offset:11264
	ds_read_b128 v[82:85], v22 offset:11776
	v_add_f32_dpp v50, v50, v50 row_ror:2 row_mask:0xf bank_mask:0xf bound_ctrl:1
	ds_read_b128 v[114:117], v22 offset:12032
	ds_read_b32 v138, v23 offset:11520
	v_add_f32_dpp v50, v50, v50 row_ror:1 row_mask:0xf bank_mask:0xf bound_ctrl:1
	v_pk_fma_f32 v[14:15], v[50:51], v[118:119], v[94:95] op_sel_hi:[0,1,1] neg_lo:[1,0,0] neg_hi:[1,0,0]
	v_pk_fma_f32 v[16:17], v[50:51], v[120:121], v[134:135] op_sel_hi:[0,1,1] neg_lo:[1,0,0] neg_hi:[1,0,0]
	v_pk_mul_f32 v[94:95], v[14:15], v[130:131]
	s_waitcnt lgkmcnt(6)
	v_pk_mul_f32 v[90:91], v[14:15], v[78:79]
	v_pk_fma_f32 v[94:95], v[16:17], v[132:133], v[94:95]
	v_pk_fma_f32 v[90:91], v[16:17], v[80:81], v[90:91]
	v_add_f32_e32 v45, v94, v95
	v_pk_fma_f32 v[94:95], v[86:87], v[14:15], v[14:15] neg_lo:[1,0,0] neg_hi:[1,0,0]
	v_pk_fma_f32 v[134:135], v[88:89], v[16:17], v[16:17] neg_lo:[1,0,0] neg_hi:[1,0,0]
	v_add_f32_e32 v50, v90, v91
	v_pk_fma_f32 v[94:95], v[136:137], v[102:103], v[94:95] op_sel_hi:[0,1,1]
	v_pk_fma_f32 v[134:135], v[136:137], v[104:105], v[134:135] op_sel_hi:[0,1,1]
	v_add_f32_dpp v50, v50, v50 row_ror:8 row_mask:0xf bank_mask:0xf bound_ctrl:1
	ds_read_b128 v[130:133], v22 offset:12288
	ds_read_b128 v[86:89], v22 offset:12544
	v_add_f32_dpp v50, v50, v50 row_ror:4 row_mask:0xf bank_mask:0xf bound_ctrl:1
	ds_read_b128 v[102:105], v22 offset:12800
	ds_read_b128 v[78:81], v22 offset:13312
	v_add_f32_dpp v50, v50, v50 row_ror:2 row_mask:0xf bank_mask:0xf bound_ctrl:1
	ds_read_b128 v[118:121], v22 offset:13568
	ds_read_b32 v136, v23 offset:13056
	v_add_f32_dpp v50, v50, v50 row_ror:1 row_mask:0xf bank_mask:0xf bound_ctrl:1
	v_pk_fma_f32 v[14:15], v[50:51], v[110:111], v[94:95] op_sel_hi:[0,1,1] neg_lo:[1,0,0] neg_hi:[1,0,0]
	v_pk_fma_f32 v[16:17], v[50:51], v[112:113], v[134:135] op_sel_hi:[0,1,1] neg_lo:[1,0,0] neg_hi:[1,0,0]
	v_pk_mul_f32 v[94:95], v[14:15], v[122:123]
	s_waitcnt lgkmcnt(6)
; #define LO2(v4) (__builtin_shufflevector(v4, v4, 0, 1))
; #define HI2(v4) (__builtin_shufflevector(v4, v4, 2, 3))
; __device__ __forceinline__ f32x2 fma2(f32x2 a, f32x2 b, f32x2 c) { return __builtin_elementwise_fma(a, b, c); }
; #define WKV_LOAD(d, s) do { const LAS float* p_ = bw + (s) * SCW; d.r = *(const LAS f32x4*)(p_); d.u = *(const LAS f32x4*)(p_ + 64); d.km = *(const LAS f32x4*)(p_ + 128); \
;                     d.kk = *(const LAS f32x4*)(p_ + 256); d.ka = *(const LAS f32x4*)(p_ + 320); d.v = bv[(s) * SCW]; } while (0)
; __device__ __forceinline__ void scan_phase(const Args& a, int e, LAS unsigned char* lds) {
;     ...
;                 for (int s = 0; s < TC; ++s) {
;                     if (s + 2 < TC) WKV_LOAD(in[(s + 2) % 3], s + 2);
;                     __builtin_amdgcn_sched_barrier(0);
;                     const WkvIn& x = in[s % 3];
;                     const f32x2 vv = {x.v, x.v};
;                     const f32x2 s2 = fma2(P1, HI2(x.kk), P0 * LO2(x.kk));
;                     const f32x2 T0 = fma2(vv, LO2(x.km), fma2(-LO2(x.u), P0, P0)), T1 = fma2(vv, HI2(x.km), fma2(-HI2(x.u), P1, P1));
;                     const float sa = rowsum16(s2.x + s2.y);
;                     const f32x2 ns = {-sa, -sa};
;                     P0 = fma2(ns, LO2(x.ka), T0); P1 = fma2(ns, HI2(x.ka), T1);
;                     const f32x2 o2 = fma2(P1, HI2(x.r), P0 * LO2(x.r));
;                     op[s] = o2.x + o2.y;
;                 }
	v_pk_mul_f32 v[90:91], v[14:15], v[82:83]
	v_pk_fma_f32 v[94:95], v[16:17], v[124:125], v[94:95]
	v_pk_fma_f32 v[90:91], v[16:17], v[84:85], v[90:91]
	v_add_f32_e32 v48, v94, v95
	v_pk_fma_f32 v[94:95], v[98:99], v[14:15], v[14:15] neg_lo:[1,0,0] neg_hi:[1,0,0]
	v_pk_fma_f32 v[134:135], v[100:101], v[16:17], v[16:17] neg_lo:[1,0,0] neg_hi:[1,0,0]
	v_add_f32_e32 v50, v90, v91
	v_pk_fma_f32 v[94:95], v[138:139], v[106:107], v[94:95] op_sel_hi:[0,1,1]
	v_pk_fma_f32 v[134:135], v[138:139], v[108:109], v[134:135] op_sel_hi:[0,1,1]
	v_add_f32_dpp v50, v50, v50 row_ror:8 row_mask:0xf bank_mask:0xf bound_ctrl:1
	ds_read_b128 v[122:125], v22 offset:13824
	ds_read_b128 v[98:101], v22 offset:14080
	v_add_f32_dpp v50, v50, v50 row_ror:4 row_mask:0xf bank_mask:0xf bound_ctrl:1
	ds_read_b128 v[106:109], v22 offset:14336
	ds_read_b128 v[82:85], v22 offset:14848
	v_add_f32_dpp v50, v50, v50 row_ror:2 row_mask:0xf bank_mask:0xf bound_ctrl:1
	ds_read_b128 v[110:113], v22 offset:15104
	ds_read_b32 v138, v23 offset:14592
	v_add_f32_dpp v50, v50, v50 row_ror:1 row_mask:0xf bank_mask:0xf bound_ctrl:1
	v_pk_fma_f32 v[14:15], v[50:51], v[114:115], v[94:95] op_sel_hi:[0,1,1] neg_lo:[1,0,0] neg_hi:[1,0,0]
	v_pk_fma_f32 v[16:17], v[50:51], v[116:117], v[134:135] op_sel_hi:[0,1,1] neg_lo:[1,0,0] neg_hi:[1,0,0]
	v_pk_mul_f32 v[94:95], v[14:15], v[126:127]
	s_waitcnt lgkmcnt(6)
	v_pk_mul_f32 v[90:91], v[14:15], v[78:79]
	v_pk_fma_f32 v[94:95], v[16:17], v[128:129], v[94:95]
	v_pk_fma_f32 v[90:91], v[16:17], v[80:81], v[90:91]
	v_add_f32_e32 v49, v94, v95
	v_pk_fma_f32 v[94:95], v[86:87], v[14:15], v[14:15] neg_lo:[1,0,0] neg_hi:[1,0,0]
	v_pk_fma_f32 v[134:135], v[88:89], v[16:17], v[16:17] neg_lo:[1,0,0] neg_hi:[1,0,0]
	v_add_f32_e32 v50, v90, v91
	v_pk_fma_f32 v[94:95], v[136:137], v[102:103], v[94:95] op_sel_hi:[0,1,1]
	v_pk_fma_f32 v[134:135], v[136:137], v[104:105], v[134:135] op_sel_hi:[0,1,1]
	v_add_f32_dpp v50, v50, v50 row_ror:8 row_mask:0xf bank_mask:0xf bound_ctrl:1
	ds_read_b128 v[126:129], v22 offset:15360
	ds_read_b128 v[86:89], v22 offset:15616
	v_add_f32_dpp v50, v50, v50 row_ror:4 row_mask:0xf bank_mask:0xf bound_ctrl:1
	ds_read_b128 v[102:105], v22 offset:15872
	ds_read_b128 v[78:81], v22 offset:16384
	v_add_f32_dpp v50, v50, v50 row_ror:2 row_mask:0xf bank_mask:0xf bound_ctrl:1
	ds_read_b128 v[114:117], v22 offset:16640
	ds_read_b32 v136, v23 offset:16128
	v_add_f32_dpp v50, v50, v50 row_ror:1 row_mask:0xf bank_mask:0xf bound_ctrl:1
	v_pk_fma_f32 v[14:15], v[50:51], v[118:119], v[94:95] op_sel_hi:[0,1,1] neg_lo:[1,0,0] neg_hi:[1,0,0]
	v_pk_fma_f32 v[16:17], v[50:51], v[120:121], v[134:135] op_sel_hi:[0,1,1] neg_lo:[1,0,0] neg_hi:[1,0,0]
	v_pk_mul_f32 v[94:95], v[14:15], v[130:131]
	s_waitcnt lgkmcnt(6)
	v_pk_mul_f32 v[90:91], v[14:15], v[82:83]
	v_pk_fma_f32 v[94:95], v[16:17], v[132:133], v[94:95]
	v_pk_fma_f32 v[90:91], v[16:17], v[84:85], v[90:91]
	v_add_f32_e32 v137, v94, v95
	v_pk_fma_f32 v[94:95], v[98:99], v[14:15], v[14:15] neg_lo:[1,0,0] neg_hi:[1,0,0]
	v_pk_fma_f32 v[134:135], v[100:101], v[16:17], v[16:17] neg_lo:[1,0,0] neg_hi:[1,0,0]
	v_add_f32_e32 v50, v90, v91
	v_pk_fma_f32 v[94:95], v[138:139], v[106:107], v[94:95] op_sel_hi:[0,1,1]
	v_pk_fma_f32 v[134:135], v[138:139], v[108:109], v[134:135] op_sel_hi:[0,1,1]
	v_add_f32_dpp v50, v50, v50 row_ror:8 row_mask:0xf bank_mask:0xf bound_ctrl:1
	ds_read_b128 v[130:133], v22 offset:16896
	ds_read_b128 v[98:101], v22 offset:17152
	v_add_f32_dpp v50, v50, v50 row_ror:4 row_mask:0xf bank_mask:0xf bound_ctrl:1
	ds_read_b128 v[106:109], v22 offset:17408
	ds_read_b128 v[82:85], v22 offset:17920
	v_add_f32_dpp v50, v50, v50 row_ror:2 row_mask:0xf bank_mask:0xf bound_ctrl:1
	ds_read_b128 v[118:121], v22 offset:18176
	ds_read_b32 v138, v23 offset:17664
	v_add_f32_dpp v50, v50, v50 row_ror:1 row_mask:0xf bank_mask:0xf bound_ctrl:1
	v_pk_fma_f32 v[14:15], v[50:51], v[110:111], v[94:95] op_sel_hi:[0,1,1] neg_lo:[1,0,0] neg_hi:[1,0,0]
	v_pk_fma_f32 v[16:17], v[50:51], v[112:113], v[134:135] op_sel_hi:[0,1,1] neg_lo:[1,0,0] neg_hi:[1,0,0]
	v_pk_mul_f32 v[94:95], v[14:15], v[122:123]
	s_waitcnt lgkmcnt(6)
	v_pk_mul_f32 v[90:91], v[14:15], v[78:79]
	v_pk_fma_f32 v[94:95], v[16:17], v[124:125], v[94:95]
	v_pk_fma_f32 v[90:91], v[16:17], v[80:81], v[90:91]
	v_add_f32_e32 v139, v94, v95
	v_pk_fma_f32 v[94:95], v[86:87], v[14:15], v[14:15] neg_lo:[1,0,0] neg_hi:[1,0,0]
	v_pk_fma_f32 v[134:135], v[88:89], v[16:17], v[16:17] neg_lo:[1,0,0] neg_hi:[1,0,0]
	v_add_f32_e32 v50, v90, v91
	v_pk_fma_f32 v[94:95], v[136:137], v[102:103], v[94:95] op_sel_hi:[0,1,1]
	v_pk_fma_f32 v[134:135], v[136:137], v[104:105], v[134:135] op_sel_hi:[0,1,1]
	v_add_f32_dpp v50, v50, v50 row_ror:8 row_mask:0xf bank_mask:0xf bound_ctrl:1
	ds_read_b128 v[122:125], v22 offset:18432
	ds_read_b128 v[86:89], v22 offset:18688
	v_add_f32_dpp v50, v50, v50 row_ror:4 row_mask:0xf bank_mask:0xf bound_ctrl:1
	ds_read_b128 v[102:105], v22 offset:18944
	ds_read_b128 v[78:81], v22 offset:19456
	v_add_f32_dpp v50, v50, v50 row_ror:2 row_mask:0xf bank_mask:0xf bound_ctrl:1
	ds_read_b128 v[110:113], v22 offset:19712
	ds_read_b32 v136, v23 offset:19200
	v_add_f32_dpp v50, v50, v50 row_ror:1 row_mask:0xf bank_mask:0xf bound_ctrl:1
	v_pk_fma_f32 v[14:15], v[50:51], v[114:115], v[94:95] op_sel_hi:[0,1,1] neg_lo:[1,0,0] neg_hi:[1,0,0]
	v_pk_fma_f32 v[16:17], v[50:51], v[116:117], v[134:135] op_sel_hi:[0,1,1] neg_lo:[1,0,0] neg_hi:[1,0,0]
	v_pk_mul_f32 v[94:95], v[14:15], v[126:127]
	s_waitcnt lgkmcnt(6)
; #define LO2(v4) (__builtin_shufflevector(v4, v4, 0, 1))
; #define HI2(v4) (__builtin_shufflevector(v4, v4, 2, 3))
; __device__ __forceinline__ f32x2 fma2(f32x2 a, f32x2 b, f32x2 c) { return __builtin_elementwise_fma(a, b, c); }
; #define WKV_LOAD(d, s) do { const LAS float* p_ = bw + (s) * SCW; d.r = *(const LAS f32x4*)(p_); d.u = *(const LAS f32x4*)(p_ + 64); d.km = *(const LAS f32x4*)(p_ + 128); \
;                     d.kk = *(const LAS f32x4*)(p_ + 256); d.ka = *(const LAS f32x4*)(p_ + 320); d.v = bv[(s) * SCW]; } while (0)
; __device__ __forceinline__ void scan_phase(const Args& a, int e, LAS unsigned char* lds) {
;     ...
;                 for (int s = 0; s < TC; ++s) {
;                     if (s + 2 < TC) WKV_LOAD(in[(s + 2) % 3], s + 2);
;                     __builtin_amdgcn_sched_barrier(0);
;                     const WkvIn& x = in[s % 3];
;                     const f32x2 vv = {x.v, x.v};
;                     const f32x2 s2 = fma2(P1, HI2(x.kk), P0 * LO2(x.kk));
;                     const f32x2 T0 = fma2(vv, LO2(x.km), fma2(-LO2(x.u), P0, P0)), T1 = fma2(vv, HI2(x.km), fma2(-HI2(x.u), P1, P1));
;                     const float sa = rowsum16(s2.x + s2.y);
;                     const f32x2 ns = {-sa, -sa};
;                     P0 = fma2(ns, LO2(x.ka), T0); P1 = fma2(ns, HI2(x.ka), T1);
;                     const f32x2 o2 = fma2(P1, HI2(x.r), P0 * LO2(x.r));
;                     op[s] = o2.x + o2.y;
;                 }
	v_pk_mul_f32 v[90:91], v[14:15], v[82:83]
	v_pk_fma_f32 v[94:95], v[16:17], v[128:129], v[94:95]
	v_pk_fma_f32 v[90:91], v[16:17], v[84:85], v[90:91]
	v_add_f32_e32 v141, v94, v95
	v_pk_fma_f32 v[94:95], v[98:99], v[14:15], v[14:15] neg_lo:[1,0,0] neg_hi:[1,0,0]
	v_pk_fma_f32 v[134:135], v[100:101], v[16:17], v[16:17] neg_lo:[1,0,0] neg_hi:[1,0,0]
	v_add_f32_e32 v50, v90, v91
	v_pk_fma_f32 v[94:95], v[138:139], v[106:107], v[94:95] op_sel_hi:[0,1,1]
	v_pk_fma_f32 v[134:135], v[138:139], v[108:109], v[134:135] op_sel_hi:[0,1,1]
	v_add_f32_dpp v50, v50, v50 row_ror:8 row_mask:0xf bank_mask:0xf bound_ctrl:1
	ds_read_b128 v[126:129], v22 offset:19968
	ds_read_b128 v[98:101], v22 offset:20224
	v_add_f32_dpp v50, v50, v50 row_ror:4 row_mask:0xf bank_mask:0xf bound_ctrl:1
	ds_read_b128 v[106:109], v22 offset:20480
	ds_read_b128 v[82:85], v22 offset:20992
	v_add_f32_dpp v50, v50, v50 row_ror:2 row_mask:0xf bank_mask:0xf bound_ctrl:1
	ds_read_b128 v[114:117], v22 offset:21248
	ds_read_b32 v138, v23 offset:20736
	v_add_f32_dpp v50, v50, v50 row_ror:1 row_mask:0xf bank_mask:0xf bound_ctrl:1
	v_pk_fma_f32 v[14:15], v[50:51], v[118:119], v[94:95] op_sel_hi:[0,1,1] neg_lo:[1,0,0] neg_hi:[1,0,0]
	v_pk_fma_f32 v[16:17], v[50:51], v[120:121], v[134:135] op_sel_hi:[0,1,1] neg_lo:[1,0,0] neg_hi:[1,0,0]
	v_pk_mul_f32 v[94:95], v[14:15], v[130:131]
	s_waitcnt lgkmcnt(6)
	v_pk_mul_f32 v[90:91], v[14:15], v[78:79]
	v_pk_fma_f32 v[94:95], v[16:17], v[132:133], v[94:95]
	v_pk_fma_f32 v[90:91], v[16:17], v[80:81], v[90:91]
	v_add_f32_e32 v142, v94, v95
	v_pk_fma_f32 v[94:95], v[86:87], v[14:15], v[14:15] neg_lo:[1,0,0] neg_hi:[1,0,0]
	v_pk_fma_f32 v[134:135], v[88:89], v[16:17], v[16:17] neg_lo:[1,0,0] neg_hi:[1,0,0]
	v_add_f32_e32 v50, v90, v91
	v_pk_fma_f32 v[94:95], v[136:137], v[102:103], v[94:95] op_sel_hi:[0,1,1]
	v_pk_fma_f32 v[134:135], v[136:137], v[104:105], v[134:135] op_sel_hi:[0,1,1]
	v_add_f32_dpp v50, v50, v50 row_ror:8 row_mask:0xf bank_mask:0xf bound_ctrl:1
	ds_read_b128 v[130:133], v22 offset:21504
	ds_read_b128 v[86:89], v22 offset:21760
	v_add_f32_dpp v50, v50, v50 row_ror:4 row_mask:0xf bank_mask:0xf bound_ctrl:1
	ds_read_b128 v[102:105], v22 offset:22016
	ds_read_b128 v[78:81], v22 offset:22528
	v_add_f32_dpp v50, v50, v50 row_ror:2 row_mask:0xf bank_mask:0xf bound_ctrl:1
	ds_read_b128 v[118:121], v22 offset:22784
	ds_read_b32 v136, v23 offset:22272
	v_add_f32_dpp v50, v50, v50 row_ror:1 row_mask:0xf bank_mask:0xf bound_ctrl:1
	v_pk_fma_f32 v[14:15], v[50:51], v[110:111], v[94:95] op_sel_hi:[0,1,1] neg_lo:[1,0,0] neg_hi:[1,0,0]
	v_pk_fma_f32 v[16:17], v[50:51], v[112:113], v[134:135] op_sel_hi:[0,1,1] neg_lo:[1,0,0] neg_hi:[1,0,0]
	v_pk_mul_f32 v[94:95], v[14:15], v[122:123]
	s_waitcnt lgkmcnt(6)
	v_pk_mul_f32 v[90:91], v[14:15], v[82:83]
	v_pk_fma_f32 v[94:95], v[16:17], v[124:125], v[94:95]
	v_pk_fma_f32 v[90:91], v[16:17], v[84:85], v[90:91]
	v_add_f32_e32 v140, v94, v95
	s_lshl_b32 s15, s14, 4
	s_xor_b32 s15, s15, 16
	v_or_b32_e32 v93, s15, v54
	v_add_u32_e32 v97, s15, v53
	v_add_u32_e32 v51, s15, v31
	v_mad_u32_u24 v93, v93, v67, v68
	v_mad_u32_u24 v97, v97, v67, v69
	v_mad_u32_u24 v51, v51, v67, v70
	v_pk_fma_f32 v[94:95], v[98:99], v[14:15], v[14:15] neg_lo:[1,0,0] neg_hi:[1,0,0]
	v_pk_fma_f32 v[134:135], v[100:101], v[16:17], v[16:17] neg_lo:[1,0,0] neg_hi:[1,0,0]
	v_add_f32_e32 v50, v90, v91
	v_pk_fma_f32 v[94:95], v[138:139], v[106:107], v[94:95] op_sel_hi:[0,1,1]
	v_pk_fma_f32 v[134:135], v[138:139], v[108:109], v[134:135] op_sel_hi:[0,1,1]
	v_add_f32_dpp v50, v50, v50 row_ror:8 row_mask:0xf bank_mask:0xf bound_ctrl:1
	ds_read_b128 v[122:125], v22 offset:23040
	ds_read_b128 v[98:101], v22 offset:23296
	v_add_f32_dpp v50, v50, v50 row_ror:4 row_mask:0xf bank_mask:0xf bound_ctrl:1
	ds_read_b128 v[106:109], v22 offset:23552
	ds_read_b128 v[82:85], v22 offset:24064
	v_add_f32_dpp v50, v50, v50 row_ror:2 row_mask:0xf bank_mask:0xf bound_ctrl:1
	ds_read_b128 v[110:113], v22 offset:24320
	ds_read_b32 v138, v23 offset:23808
	v_add_f32_dpp v50, v50, v50 row_ror:1 row_mask:0xf bank_mask:0xf bound_ctrl:1
	v_pk_fma_f32 v[14:15], v[50:51], v[114:115], v[94:95] op_sel_hi:[0,1,1] neg_lo:[1,0,0] neg_hi:[1,0,0]
	v_pk_fma_f32 v[16:17], v[50:51], v[116:117], v[134:135] op_sel_hi:[0,1,1] neg_lo:[1,0,0] neg_hi:[1,0,0]
	v_pk_mul_f32 v[94:95], v[14:15], v[126:127]
	s_waitcnt lgkmcnt(6)
	v_pk_mul_f32 v[90:91], v[14:15], v[78:79]
	v_pk_fma_f32 v[94:95], v[16:17], v[128:129], v[94:95]
	v_pk_fma_f32 v[90:91], v[16:17], v[80:81], v[90:91]
	v_add_f32_e32 v96, v94, v95
	s_waitcnt vmcnt(0)
	v_lshlrev_b32_e32 v114, 16, v6
	v_and_b32_e32 v115, 0xffff0000, v6
	v_lshlrev_b32_e32 v116, 16, v7
	v_and_b32_e32 v117, 0xffff0000, v7
	v_lshlrev_b32_e32 v126, 16, v8
	v_and_b32_e32 v127, 0xffff0000, v8
	v_lshlrev_b32_e32 v128, 16, v9
	v_and_b32_e32 v129, 0xffff0000, v9
	v_pk_fma_f32 v[94:95], v[86:87], v[14:15], v[14:15] neg_lo:[1,0,0] neg_hi:[1,0,0]
	v_pk_fma_f32 v[134:135], v[88:89], v[16:17], v[16:17] neg_lo:[1,0,0] neg_hi:[1,0,0]
	v_add_f32_e32 v50, v90, v91
	v_pk_fma_f32 v[94:95], v[136:137], v[102:103], v[94:95] op_sel_hi:[0,1,1]
	v_pk_fma_f32 v[134:135], v[136:137], v[104:105], v[134:135] op_sel_hi:[0,1,1]
	v_add_f32_dpp v50, v50, v50 row_ror:8 row_mask:0xf bank_mask:0xf bound_ctrl:1
	s_nop 1
	v_add_f32_dpp v50, v50, v50 row_ror:4 row_mask:0xf bank_mask:0xf bound_ctrl:1
	s_nop 1
	v_add_f32_dpp v50, v50, v50 row_ror:2 row_mask:0xf bank_mask:0xf bound_ctrl:1
	s_nop 1
	v_add_f32_dpp v50, v50, v50 row_ror:1 row_mask:0xf bank_mask:0xf bound_ctrl:1
	v_pk_fma_f32 v[14:15], v[50:51], v[118:119], v[94:95] op_sel_hi:[0,1,1] neg_lo:[1,0,0] neg_hi:[1,0,0]
	v_pk_fma_f32 v[16:17], v[50:51], v[120:121], v[134:135] op_sel_hi:[0,1,1] neg_lo:[1,0,0] neg_hi:[1,0,0]
	v_pk_mul_f32 v[94:95], v[14:15], v[130:131]
	s_waitcnt lgkmcnt(0)
; #define TR_DPP(x, ctrl) __builtin_bit_cast(float, __builtin_amdgcn_update_dpp(0, __builtin_bit_cast(int, x), ctrl, 0xf, 0xf, false))
; __device__ __forceinline__ float transpose_reduce16(const float* p, int g) {
;     const bool h1 = (g & 8) != 0, h2 = (g & 4) != 0, h3 = (g & 2) != 0, h4 = (g & 1) != 0;
;     float q[8], r[4], t[2];
; #pragma unroll
;     for (int i = 0; i < 8; ++i) { const float keep = h1 ? p[i + 8] : p[i], send = h1 ? p[i] : p[i + 8]; q[i] = keep + TR_DPP(send, 0x140); }
; #pragma unroll
;     for (int i = 0; i < 4; ++i) { const float keep = h2 ? q[i + 4] : q[i], send = h2 ? q[i] : q[i + 4]; r[i] = keep + TR_DPP(send, 0x141); }
; #pragma unroll
;     for (int i = 0; i < 2; ++i) { const float keep = h3 ? r[i + 2] : r[i], send = h3 ? r[i] : r[i + 2]; t[i] = keep + TR_DPP(send, 0x4E); }
;     const float keep = h4 ? t[1] : t[0], send = h4 ? t[0] : t[1];
;     return keep + TR_DPP(send, 0xB1);
	v_pk_mul_f32 v[90:91], v[14:15], v[82:83]
	v_pk_fma_f32 v[94:95], v[16:17], v[132:133], v[94:95]
	v_pk_fma_f32 v[90:91], v[16:17], v[84:85], v[90:91]
	v_add_f32_e32 v92, v94, v95
	v_lshlrev_b32_e32 v78, 16, v10
	v_and_b32_e32 v79, 0xffff0000, v10
	v_lshlrev_b32_e32 v80, 16, v11
	v_and_b32_e32 v81, 0xffff0000, v11
	v_lshlrev_b32_e32 v86, 16, v12
	v_and_b32_e32 v87, 0xffff0000, v12
	v_lshlrev_b32_e32 v88, 16, v13
	v_and_b32_e32 v89, 0xffff0000, v13
	v_lshlrev_b32_e32 v102, 16, v2
	v_and_b32_e32 v103, 0xffff0000, v2
	v_lshlrev_b32_e32 v104, 16, v3
	v_and_b32_e32 v105, 0xffff0000, v3
	v_lshlrev_b32_e32 v118, 16, v4
	v_and_b32_e32 v119, 0xffff0000, v4
	v_lshlrev_b32_e32 v120, 16, v5
	v_and_b32_e32 v121, 0xffff0000, v5
	v_pk_fma_f32 v[94:95], v[98:99], v[14:15], v[14:15] neg_lo:[1,0,0] neg_hi:[1,0,0]
	v_pk_fma_f32 v[134:135], v[100:101], v[16:17], v[16:17] neg_lo:[1,0,0] neg_hi:[1,0,0]
	v_add_f32_e32 v50, v90, v91
	v_pk_fma_f32 v[94:95], v[138:139], v[106:107], v[94:95] op_sel_hi:[0,1,1]
	v_pk_fma_f32 v[134:135], v[138:139], v[108:109], v[134:135] op_sel_hi:[0,1,1]
	v_add_f32_dpp v50, v50, v50 row_ror:8 row_mask:0xf bank_mask:0xf bound_ctrl:1
	ds_write_b128 v93, v[114:117]
	ds_write_b128 v93, v[126:129] offset:16
	v_add_f32_dpp v50, v50, v50 row_ror:4 row_mask:0xf bank_mask:0xf bound_ctrl:1
	ds_write_b128 v97, v[78:81]
	ds_write_b128 v97, v[86:89] offset:16
	v_add_f32_dpp v50, v50, v50 row_ror:2 row_mask:0xf bank_mask:0xf bound_ctrl:1
	ds_write_b128 v51, v[102:105]
	ds_write_b128 v51, v[118:121] offset:16
	v_add_f32_dpp v50, v50, v50 row_ror:1 row_mask:0xf bank_mask:0xf bound_ctrl:1
	v_pk_fma_f32 v[14:15], v[50:51], v[110:111], v[94:95] op_sel_hi:[0,1,1] neg_lo:[1,0,0] neg_hi:[1,0,0]
	v_pk_fma_f32 v[16:17], v[50:51], v[112:113], v[134:135] op_sel_hi:[0,1,1] neg_lo:[1,0,0] neg_hi:[1,0,0]
	v_pk_mul_f32 v[94:95], v[14:15], v[122:123]
	s_nop 0
	v_pk_fma_f32 v[94:95], v[16:17], v[124:125], v[94:95]
	s_nop 0
	v_add_f32_e32 v22, v94, v95
	v_cndmask_b32_e64 v23, v137, v19, s[42:43]
	v_cndmask_b32_e64 v19, v19, v137, s[42:43]
	s_nop 1
	v_add_f32_dpp v19, v19, v23 row_mirror row_mask:0xf bank_mask:0xf bound_ctrl:1
	v_cndmask_b32_e64 v23, v139, v21, s[42:43]
	v_cndmask_b32_e64 v21, v21, v139, s[42:43]
	s_nop 1
	v_add_f32_dpp v21, v21, v23 row_mirror row_mask:0xf bank_mask:0xf bound_ctrl:1
	v_cndmask_b32_e64 v23, v141, v24, s[42:43]
	v_cndmask_b32_e64 v24, v24, v141, s[42:43]
	s_nop 1
	v_add_f32_dpp v23, v24, v23 row_mirror row_mask:0xf bank_mask:0xf bound_ctrl:1
	v_cndmask_b32_e64 v24, v142, v25, s[42:43]
	v_cndmask_b32_e64 v25, v25, v142, s[42:43]
	s_nop 1
	v_add_f32_dpp v24, v25, v24 row_mirror row_mask:0xf bank_mask:0xf bound_ctrl:1
	v_cndmask_b32_e64 v25, v140, v43, s[42:43]
	v_cndmask_b32_e64 v43, v43, v140, s[42:43]
	s_nop 1
	v_add_f32_dpp v25, v43, v25 row_mirror row_mask:0xf bank_mask:0xf bound_ctrl:1
	v_cndmask_b32_e64 v43, v96, v45, s[42:43]
	v_cndmask_b32_e64 v45, v45, v96, s[42:43]
	s_nop 1
	v_add_f32_dpp v43, v45, v43 row_mirror row_mask:0xf bank_mask:0xf bound_ctrl:1
	v_cndmask_b32_e64 v45, v92, v48, s[42:43]
	v_cndmask_b32_e64 v48, v48, v92, s[42:43]
	s_nop 1
	v_add_f32_dpp v45, v48, v45 row_mirror row_mask:0xf bank_mask:0xf bound_ctrl:1
	v_cndmask_b32_e64 v48, v22, v49, s[42:43]
	v_cndmask_b32_e64 v22, v49, v22, s[42:43]
	s_nop 1
	v_add_f32_dpp v22, v22, v48 row_mirror row_mask:0xf bank_mask:0xf bound_ctrl:1
	v_cndmask_b32_e64 v48, v25, v19, s[44:45]
	v_cndmask_b32_e64 v19, v19, v25, s[44:45]
	v_cndmask_b32_e64 v25, v43, v21, s[44:45]
	v_cndmask_b32_e64 v21, v21, v43, s[44:45]
	v_add_f32_dpp v19, v19, v48 row_half_mirror row_mask:0xf bank_mask:0xf bound_ctrl:1
	s_nop 0
	v_add_f32_dpp v21, v21, v25 row_half_mirror row_mask:0xf bank_mask:0xf bound_ctrl:1
	v_cndmask_b32_e64 v25, v45, v23, s[44:45]
	v_cndmask_b32_e64 v23, v23, v45, s[44:45]
	s_nop 1
	v_add_f32_dpp v23, v23, v25 row_half_mirror row_mask:0xf bank_mask:0xf bound_ctrl:1
	v_cndmask_b32_e64 v25, v22, v24, s[44:45]
	v_cndmask_b32_e64 v22, v24, v22, s[44:45]
	v_cndmask_b32_e64 v24, v23, v19, s[46:47]
	v_cndmask_b32_e64 v19, v19, v23, s[46:47]
	v_add_f32_dpp v22, v22, v25 row_half_mirror row_mask:0xf bank_mask:0xf bound_ctrl:1
	s_nop 0
	v_add_f32_dpp v23, v19, v24 quad_perm:[2,3,0,1] row_mask:0xf bank_mask:0xf bound_ctrl:1
	v_cndmask_b32_e64 v19, v22, v21, s[46:47]
	v_cndmask_b32_e64 v21, v21, v22, s[46:47]
	s_nop 1
	v_add_f32_dpp v21, v21, v19 quad_perm:[2,3,0,1] row_mask:0xf bank_mask:0xf bound_ctrl:1
	v_cndmask_b32_e64 v19, v21, v23, s[48:49]
	v_cndmask_b32_e64 v22, v23, v21, s[48:49]
	v_mov_b32_e32 v21, v1
	s_nop 1
	v_mov_b32_dpp v21, v22 quad_perm:[1,0,3,2] row_mask:0xf bank_mask:0xf
